# grid barrier between P7 and P8 dropped: P8 walks units in P7's order (same workgroup consumes its own T1 tiles), sample accumulator through a release/acquire counter
# baseline (speedup 1.0000x reference)
; #define PG8_WAIT_V(n) asm volatile("s_waitcnt vmcnt(" #n ")" ::: "memory")
; #define PG8_BAR __builtin_amdgcn_s_barrier()
; #define GRID_BAR() xcd_barrier(bar)
; #define GEMM_SMP(EPI, AOFF, BOFF, NN, KK, PP_, ...) do { pg8::Gemm g{(bf16*)(ws + (AOFF)), (bf16*)(ws + (BOFF)), M_PAD, (NN), (KK) / (PP_), (KK)}; pg8::SampOrder S; S.init((NN), (PP_), (KK) / (PP_), F.G, bx); EPI E{__VA_ARGS__}; \
;         pg8::gemm_phase<EPI, pg8::SampOrder, true, true, true>(F.lds + RING_OFF, g, S, E); } while (0)
; template <class Epi, class Sched, bool ALIGN_EPI = false, bool SP2 = false, bool HALFM = false>
; __device__ __forceinline__ void gemm_phase(PG8_LAS unsigned char* lds, const Gemm g, const Sched& S, const Epi& E) {
;     ...
;     PG8_WAIT_V(0);
;     if constexpr (!ALIGN_EPI) { if (wr == 0) PG8_BAR; }
;     PG8_BAR;
; __global__ void __launch_bounds__(NWAVES * 64, 2) fwd(Args args) {
;     ...
;     GEMM_SMP(pg8::EpiOssmAt, WS_YG, WS_WOS, 1024, 2048, 8, (float*)(ws + WS_T1S), (bf16*)(ws + WS_GS), (const float*)(ws + WS_RSTD));
;     GRID_BAR();
.LBB0_1530:
	s_waitcnt vmcnt(0)
	s_barrier
	buffer_wbl2 sc1
	s_waitcnt vmcnt(0) lgkmcnt(0)
	s_mov_b64 s[4:5], exec
	v_readlane_b32 s0, v254, 6
	v_readlane_b32 s1, v254, 7
	s_and_b64 s[0:1], s[4:5], s[0:1]
	s_mov_b64 exec, s[0:1]
	s_cbranch_execz .Lp7_rel_done
	v_mov_b32_e32 v1, 0
	v_mov_b32_e32 v2, 1
	buffer_wbl2 sc1
	s_waitcnt vmcnt(0)
	global_atomic_add v1, v2, s[96:97] offset:268

; __device__ __forceinline__ unsigned xb_ld(unsigned* p)              { return __hip_atomic_load(p, __ATOMIC_RELAXED, __HIP_MEMORY_SCOPE_AGENT); }
; __device__ __forceinline__ unsigned xb_add(unsigned* p, unsigned v) { return __hip_atomic_fetch_add(p, v, __ATOMIC_RELAXED, __HIP_MEMORY_SCOPE_AGENT); }
; #define XB_SPIN(cond, bar) do { unsigned _sp = 0; while (cond) { __builtin_amdgcn_s_sleep(1); \
;     if ((++_sp & 255u) == 0u) { if (xb_ld(&(bar)[XB_TMO])) break; if (_sp > XB_SPIN_CAP) { atomicAdd(&(bar)[XB_TMO], 1u); break; } } } } while (0)
; __device__ __forceinline__ void xcd_barrier(const XcdBarrier& b) {
;     asm volatile("s_waitcnt vmcnt(0)" ::: "memory");
;     __syncthreads();
;     if (threadIdx.x == 0) {
;         unsigned* bar = b.bar;
;         __builtin_amdgcn_s_waitcnt(0);
;         unsigned nloc = b.st[0], nx = b.st[1];
;         if (nloc == 0u) { xcd_barrier_complete(bar, b.x, nloc, nx); b.st[0] = nloc; b.st[1] = nx; }
;         const unsigned old = xb_add(&bar[XB_XSUB(b.x)], 1u);
;         const unsigned gen = old / nloc;
;         if (old + 1u == (gen + 1u) * nloc) {
;             __builtin_amdgcn_fence(__ATOMIC_RELEASE, "agent");
;             asm volatile("s_waitcnt vmcnt(0)" ::: "memory");
;             const unsigned og = xb_add(&bar[XB_TOP], 1u);
;             const unsigned tg = og / nx;
;             if (og + 1u == (tg + 1u) * nx) xb_add(&bar[XB_TOPGEN], 1u);
;             else XB_SPIN(xb_ld(&bar[XB_TOPGEN]) == tg, bar);
;             __builtin_amdgcn_fence(__ATOMIC_ACQUIRE, "agent");
;             xb_add(&bar[XB_XGEN(b.x)], 1u);
;             asm volatile("s_waitcnt vmcnt(0)" ::: "memory");
;         } else {
;             XB_SPIN(xb_ld(&bar[XB_XGEN(b.x)]) == gen, bar);
;             __builtin_amdgcn_fence(__ATOMIC_ACQUIRE, "agent");
;             asm volatile("s_waitcnt vmcnt(0)" ::: "memory");
;         }
;     }
;     __syncthreads();
; }
.LBB0_1531:
	s_waitcnt vmcnt(0)
	s_waitcnt lgkmcnt(0)
	s_barrier
	s_mov_b64 s[4:5], exec
	v_readlane_b32 s0, v254, 6
	v_readlane_b32 s1, v254, 7
	s_and_b64 s[0:1], s[4:5], s[0:1]
	s_mov_b64 exec, s[0:1]
	s_branch .LBB0_1583
	s_add_i32 s0, 0, 0x22160
	v_mov_b32_e32 v1, s0
	s_waitcnt vmcnt(0) expcnt(0) lgkmcnt(0)
	ds_read_b32 v3, v1
	s_add_i32 s0, 0, 0x22164
	v_mov_b32_e32 v1, s0
	ds_read_b32 v1, v1
	s_waitcnt lgkmcnt(1)
	v_cmp_ne_u32_e32 vcc, 0, v3
	s_cbranch_vccnz .LBB0_1547
	s_add_u32 s6, s96, 0x4200
	s_addc_u32 s7, s97, 0
	s_add_u32 s12, s96, 0x4400
	s_addc_u32 s13, s97, 0
	s_add_u32 s14, s96, 0x4500
	s_addc_u32 s15, s97, 0
	s_add_u32 s18, s96, 0x4600
	s_addc_u32 s19, s97, 0
	s_add_u32 s20, s96, 0x4700
	s_addc_u32 s21, s97, 0
	s_add_u32 s22, s96, 0x4800
	s_addc_u32 s23, s97, 0
	s_add_u32 s24, s96, 0x4900
	s_addc_u32 s25, s97, 0
	s_add_u32 s26, s96, 0x4a00
	s_addc_u32 s27, s97, 0
	s_add_u32 s28, s96, 0x4b00
	s_addc_u32 s29, s97, 0
	s_add_u32 s30, s96, 0x4c00
	s_addc_u32 s31, s97, 0
	s_add_u32 s34, s96, 0x4d00
	s_addc_u32 s35, s97, 0
	s_add_u32 s36, s96, 0x4e00
	s_addc_u32 s37, s97, 0
	s_add_u32 s38, s96, 0x4f00
	v_readlane_b32 s2, v254, 0
	s_addc_u32 s39, s97, 0
	v_readlane_b32 s3, v254, 1
	s_add_u32 s40, s96, 0x5000
	s_load_dwordx2 s[0:1], s[2:3], 0x4
	s_addc_u32 s41, s97, 0
	s_add_u32 s42, s96, 0x5100
	s_addc_u32 s43, s97, 0
	s_add_u32 s44, s96, 0x5200
	s_addc_u32 s45, s97, 0
	s_waitcnt lgkmcnt(0)
	s_mul_i32 s0, s0, s33
	s_add_u32 s46, s96, 0x5300
	s_mul_i32 s0, s0, s1
	s_addc_u32 s47, s97, 0
	s_mov_b32 s1, 1
	v_mov_b32_e32 v17, 0
	s_branch .LBB0_1535

;     __host__ __device__ bool next(int i, Unit& u) const {
;         const long L = (long)i * G + c; if (L >= nwg) return false;
;         int wgid = (int)L; { const int q = nwg / NXCD, r = nwg % NXCD, xcd = wgid % NXCD, off = wgid / NXCD; wgid = (xcd < r ? xcd * (q + 1) : r * (q + 1) + (xcd - r) * q) + off; }
;         const int nig = WGM * nN, gid = wgid / nig, fm = gid * WGM, gsz = (nM - fm) < WGM ? (nM - fm) : WGM;
;         const int pm = fm + ((wgid % nig) % gsz); u.pm = rev ? nM - 1 - pm : pm; u.pn = (wgid % nig) / gsz; u.ko = 0; return true;
;     }
; template <class Epi, class Sched, bool ALIGN_EPI = false, bool SP2 = false, bool HALFM = false>
; __device__ __forceinline__ void gemm_phase(PG8_LAS unsigned char* lds, const Gemm g, const Sched& S, const Epi& E) {
;     ...
;     for (int i = 0; i < 2; ++i) { int R, C; stage_rc(tid * 16 + i * 8192, R, C); const int Rb = Epi::PERM ? ((R & ~31) + perm32(R & 31)) : R;
;         voffA[i] = (unsigned)(R * g.ld + C) * 2u; voffB[i] = (unsigned)(Rb * g.ld + C) * 2u; }
;     const size_t kstep = (size_t)(BK * 2);
;     const size_t hstep = (size_t)HALF * g.ld * 2;
;     const size_t tstep = 2 * hstep;
;     const unsigned ldsw = (unsigned)wid * 1024u;
;     const int aoff = lds_byte(wr * 64 + fr, fq * 8), boff = lds_byte(wc * 32 + fr, fq * 8);
;     ...
;     const char* cA = (const char*)g.A + (size_t)cur.pm * tstep + (size_t)cur.ko * 2; const char* cB = (const char*)g.Bt + (size_t)cur.pn * tstep + (size_t)cur.ko * 2;
;     S.a_ready(cur);
;     if constexpr (SP2) {
;         PG8_STAGE(PG8_SB(0, 0), cB, voffB); PG8_STAGE(PG8_SB(0, 1), cB + hstep, voffB); PG8_STAGE(PG8_SA(0, 0), cA, voffA); PG8_STAGE(PG8_SA(0, 1), cA + hstep, voffA);
;         if (wr == 1) PG8_BAR;
;         PG8_WAIT_V(2); PG8_BAR;
;         PG8_STAGE(PG8_SB(1, 0), cB + kstep, voffB); PG8_STAGE(PG8_SA(1, 0), cA + kstep, voffA); PG8_STAGE(PG8_SB(1, 1), cB + hstep + kstep, voffB);
;         PG8_WAIT_V(6); PG8_BAR;
;     } else {
;         PG8_STAGE(PG8_SB(0, 0), cB, voffB); PG8_STAGE(PG8_SA(0, 0), cA, voffA); PG8_STAGE(PG8_SB(0, 1), cB + hstep, voffB); PG8_STAGE(PG8_SA(0, 1), cA + hstep, voffA);
;         if (wr == 1) PG8_BAR;
;         PG8_WAIT_V(4); PG8_BAR;
;         PG8_STAGE(PG8_SB(1, 0), cB + kstep, voffB); PG8_STAGE(PG8_SA(1, 0), cA + kstep, voffA); PG8_STAGE(PG8_SB(1, 1), cB + hstep + kstep, voffB);
;         PG8_WAIT_V(6); PG8_BAR;
.LBB0_1588:
	v_ashrrev_i32_e32 v2, 31, v10
	v_lshrrev_b32_e32 v2, 26, v2
	v_add_u32_e32 v2, v10, v2
	v_ashrrev_i32_e32 v11, 6, v2
	v_bfe_i32 v2, v10, 27, 1
	v_lshlrev_b32_e32 v1, 4, v10
	v_lshrrev_b32_e32 v2, 22, v2
	v_add_u32_e32 v2, v1, v2
	v_and_b32_e32 v2, 0xfffffc00, v2
	v_sub_u32_e32 v2, v1, v2
	v_lshrrev_b32_e32 v3, 4, v2
	v_bitop3_b32 v2, v3, v2, 32 bitop3:0x6c
	v_ashrrev_i32_e32 v4, 31, v2
	v_lshrrev_b32_e32 v4, 26, v4
	v_add_u32_e32 v4, v2, v4
	v_lshlrev_b32_e32 v3, 3, v11
	v_ashrrev_i32_e32 v12, 6, v4
	v_and_b32_e32 v4, 0xc0, v4
	v_and_b32_e32 v3, -16, v3
	v_sub_u32_e32 v2, v2, v4
	v_mov_b32_e32 v4, 1
	v_add_u32_e32 v3, v12, v3
	v_ashrrev_i16_sdwa v2, v4, sext(v2) dst_sel:DWORD dst_unused:UNUSED_PAD src0_sel:DWORD src1_sel:BYTE_0
	s_ashr_i32 s2, s0, 3
	v_lshlrev_b32_e32 v5, 5, v11
	v_bfe_i32 v13, v2, 0, 16
	v_lshlrev_b32_e32 v2, 1, v3
	v_lshrrev_b32_e32 v6, 2, v3
	v_and_b32_e32 v7, 3, v12
	s_mov_b32 s0, 0x3fffe0
	v_and_b32_e32 v5, 32, v5
	v_and_b32_e32 v2, 24, v2
	v_and_b32_e32 v6, 4, v6
	v_and_or_b32 v7, v3, s0, v7
	v_or3_b32 v2, v7, v6, v2
	v_add_lshl_u32 v5, v5, v13, 1
	v_add_u32_e32 v1, 0x2000, v1
	v_lshl_add_u32 v152, v2, 10, v5
	v_ashrrev_i32_e32 v2, 31, v1
	s_add_i32 s1, s1, s2
	v_lshrrev_b32_e32 v2, 22, v2
	s_ashr_i32 s2, s1, 31
	v_add_u32_e32 v2, v1, v2
	s_lshr_b32 s2, s2, 27
	v_ashrrev_i32_e32 v14, 10, v2
	s_add_i32 s2, s1, s2
	v_mul_i32_i24_e32 v2, 0x400, v14
	s_ashr_i32 s3, s2, 5
	s_andn2_b32 s2, s2, 31
	v_sub_u32_e32 v1, v1, v2
	s_sub_i32 s1, s1, s2
	v_lshrrev_b32_e32 v2, 4, v1
	s_bfe_i32 s2, s1, 0x80000
	v_bitop3_b32 v1, v2, v1, 32 bitop3:0x6c
	s_bfe_u32 s2, s2, 0x3000c
	v_lshl_add_u32 v150, v3, 10, v5
	v_ashrrev_i32_e32 v3, 31, v1
	s_add_i32 s2, s1, s2
	v_lshrrev_b32_e32 v3, 26, v3
	s_bfe_i32 s4, s2, 0x80000
	s_and_b32 s2, s2, 0xf8
	v_add_u32_e32 v3, v1, v3
	s_sub_i32 s1, s1, s2
	v_lshlrev_b32_e32 v2, 3, v14
	v_ashrrev_i32_e32 v15, 6, v3
	v_and_b32_e32 v3, 0xc0, v3
	s_lshl_b32 s3, s3, 3
	s_sext_i32_i16 s4, s4
	s_sext_i32_i8 s1, s1
	v_and_b32_e32 v2, -16, v2
	v_sub_u32_e32 v1, v1, v3
	s_lshr_b32 s6, s4, 3
	s_add_i32 s34, s3, s1
	s_sub_i32 s34, 0xff, s34
	v_add_u32_e32 v2, v15, v2
	v_ashrrev_i16_sdwa v1, v4, sext(v1) dst_sel:DWORD dst_unused:UNUSED_PAD src0_sel:DWORD src1_sel:BYTE_0
	v_and_b32_e32 v4, 3, v15
	s_ashr_i32 s14, s7, 6
	s_ashr_i32 s35, s34, 31
	s_bfe_i64 s[4:5], s[6:7], 0x100000
	s_ashr_i32 s20, s7, 8
	v_and_or_b32 v4, v2, s0, v4
	s_lshl_b32 s0, s14, 10
	s_lshl_b64 s[2:3], s[34:35], 18
	s_lshl_b64 s[4:5], s[4:5], 18
	s_add_u32 s38, s63, s4
	v_lshlrev_b32_e32 v5, 5, v14
	v_bfe_i32 v16, v1, 0, 16
	v_lshlrev_b32_e32 v1, 1, v2
	v_lshrrev_b32_e32 v3, 2, v2
	s_addc_u32 s39, s64, s5
	s_add_i32 s1, s0, 0
	v_and_b32_e32 v5, 32, v5
	v_and_b32_e32 v1, 24, v1
	v_and_b32_e32 v3, 4, v3
	s_add_i32 m0, s1, 0x10000
	v_or3_b32 v1, v4, v3, v1
	v_add_lshl_u32 v3, v5, v16, 1
	global_load_lds_dwordx4 v152, s[38:39]
	s_add_i32 m0, s1, 0x12000
	v_lshl_add_u32 v156, v1, 10, v3
	s_add_u32 s4, s38, 0x20000
	global_load_lds_dwordx4 v156, s[38:39]
	s_addc_u32 s5, s39, 0
	s_add_i32 m0, s1, 0x14000
	v_lshl_add_u32 v154, v2, 10, v3
	global_load_lds_dwordx4 v152, s[4:5]
	s_add_i32 m0, s1, 0x16000
	s_add_u32 s36, s60, s2
	s_addc_u32 s37, s61, s3
	s_add_i32 s2, s1, 0x2000
	global_load_lds_dwordx4 v156, s[4:5]
	s_mov_b32 m0, s1
	s_add_u32 s4, s36, 0x20000
	global_load_lds_dwordx4 v150, s[36:37]
	s_mov_b32 m0, s2
	s_addc_u32 s5, s37, 0
	s_add_i32 s3, s1, 0x4000
	global_load_lds_dwordx4 v154, s[36:37]
	s_mov_b32 m0, s3
	s_add_i32 s35, s1, 0x6000
	global_load_lds_dwordx4 v150, s[4:5]
	s_mov_b32 m0, s35
	v_mov_b32_e32 v153, 0
	global_load_lds_dwordx4 v154, s[4:5]
	v_mov_b32_e32 v157, v153
	v_mov_b32_e32 v151, v153
	v_mov_b32_e32 v155, v153
	s_cmp_eq_u32 s20, 1
	s_mov_b32 s42, 0
	v_lshl_add_u64 v[8:9], s[38:39], 0, v[152:153]
	v_lshl_add_u64 v[6:7], s[38:39], 0, v[156:157]
	v_lshl_add_u64 v[2:3], s[36:37], 0, v[150:151]
	s_cselect_b64 s[4:5], -1, 0
	s_cmp_lg_u32 s20, 1
	v_lshl_add_u64 v[4:5], s[36:37], 0, v[154:155]
	s_cbranch_scc1 .LBB0_1590
	s_barrier

;     __device__ __forceinline__ bool next(int i, Unit& u) const { const int L = L0 + i * G + c; if (L >= L1) return false; u.pm = L >> 2; u.pn = L & 3; u.ko = 0; return true; }
;     __host__ __device__ bool next(int i, Unit& u) const {
;         const long L = (long)i * G + c; if (L >= nwg) return false;
;         int wgid = (int)L; { const int q = nwg / NXCD, r = nwg % NXCD, xcd = wgid % NXCD, off = wgid / NXCD; wgid = (xcd < r ? xcd * (q + 1) : r * (q + 1) + (xcd - r) * q) + off; }
;         const int nig = WGM * nN, gid = wgid / nig, fm = gid * WGM, gsz = (nM - fm) < WGM ? (nM - fm) : WGM;
;         const int pm = fm + ((wgid % nig) % gsz); u.pm = rev ? nM - 1 - pm : pm; u.pn = (wgid % nig) / gsz; u.ko = 0; return true;
;     }
.LBB0_1598:
	s_ashr_i32 s24, s26, 3
	s_add_i32 s24, s28, s24
	s_ashr_i32 s25, s24, 31
	s_lshr_b32 s25, s25, 27
	s_add_i32 s25, s24, s25
	s_ashr_i32 s26, s25, 5
	s_lshl_b32 s26, s26, 3
	s_sub_i32 s27, 0x100, s26
	s_min_i32 s27, s27, 8
	s_abs_i32 s28, s27
	v_cvt_f32_u32_e32 v2, s28
	s_sub_i32 s30, 0, s28
	s_andn2_b32 s25, s25, 31
	s_sub_i32 s25, s24, s25
	v_rcp_iflag_f32_e32 v2, v2
	s_abs_i32 s24, s25
	s_xor_b32 s29, s25, s27
	s_ashr_i32 s29, s29, 31
	v_mul_f32_e32 v2, 0x4f7ffffe, v2
	v_cvt_u32_f32_e32 v2, v2
	s_nop 0
	v_readfirstlane_b32 s31, v2
	s_mul_i32 s30, s30, s31
	s_mul_hi_u32 s30, s31, s30
	s_add_i32 s31, s31, s30
	s_mul_hi_u32 s30, s24, s31
	s_mul_i32 s31, s30, s28
	s_sub_i32 s24, s24, s31
	s_add_i32 s40, s30, 1
	s_sub_i32 s31, s24, s28
	s_cmp_ge_u32 s24, s28
	s_cselect_b32 s30, s40, s30
	s_cselect_b32 s24, s31, s24
	s_add_i32 s31, s30, 1
	s_cmp_ge_u32 s24, s28
	s_cselect_b32 s24, s31, s30
	s_xor_b32 s24, s24, s29
	s_sub_i32 s24, s24, s29
	s_mul_i32 s27, s24, s27
	s_sub_i32 s25, s25, s27
	s_add_i32 s26, s26, s25
	s_sub_i32 s26, 0xff, s26

; #define PG8_WAIT_V(n) asm volatile("s_waitcnt vmcnt(" #n ")" ::: "memory")
; #define PG8_BAR __builtin_amdgcn_s_barrier()
; template <class Epi, class Sched, bool ALIGN_EPI = false, bool SP2 = false, bool HALFM = false>
; __device__ __forceinline__ void gemm_phase(PG8_LAS unsigned char* lds, const Gemm g, const Sched& S, const Epi& E) {
;     ...
;     for (int i = 0; i < 2; ++i) { int R, C; stage_rc(tid * 16 + i * 8192, R, C); const int Rb = Epi::PERM ? ((R & ~31) + perm32(R & 31)) : R;
;         voffA[i] = (unsigned)(R * g.ld + C) * 2u; voffB[i] = (unsigned)(Rb * g.ld + C) * 2u; }
;     const size_t kstep = (size_t)(BK * 2);
;     const size_t hstep = (size_t)HALF * g.ld * 2;
;     const size_t tstep = 2 * hstep;
;     const unsigned ldsw = (unsigned)wid * 1024u;
;     const int aoff = lds_byte(wr * 64 + fr, fq * 8), boff = lds_byte(wc * 32 + fr, fq * 8);
;     ...
;     Unit cur, nxt; int ui = 0;
;     if (!S.next(0, cur)) return;
;     f32x4 acc[2][2][4][2];
; #pragma unroll
;     for (int a = 0; a < 2; ++a)
; #pragma unroll
;         for (int b = 0; b < 2; ++b)
; #pragma unroll
;             for (int m = 0; m < 4; ++m)
; #pragma unroll
;                 for (int n = 0; n < 2; ++n) acc[a][b][m][n] = (f32x4){0.f, 0.f, 0.f, 0.f};
;     bf16x8 At[4][2], B0[2][2], B1[2][2];
;     const char* cA = (const char*)g.A + (size_t)cur.pm * tstep + (size_t)cur.ko * 2; const char* cB = (const char*)g.Bt + (size_t)cur.pn * tstep + (size_t)cur.ko * 2;
;     S.a_ready(cur);
;     if constexpr (SP2) {
;         PG8_STAGE(PG8_SB(0, 0), cB, voffB); PG8_STAGE(PG8_SB(0, 1), cB + hstep, voffB); PG8_STAGE(PG8_SA(0, 0), cA, voffA); PG8_STAGE(PG8_SA(0, 1), cA + hstep, voffA);
;         if (wr == 1) PG8_BAR;
;         PG8_WAIT_V(2); PG8_BAR;
;         PG8_STAGE(PG8_SB(1, 0), cB + kstep, voffB); PG8_STAGE(PG8_SA(1, 0), cA + kstep, voffA); PG8_STAGE(PG8_SB(1, 1), cB + hstep + kstep, voffB);
;         PG8_WAIT_V(6); PG8_BAR;
;     } else {
;         PG8_STAGE(PG8_SB(0, 0), cB, voffB); PG8_STAGE(PG8_SA(0, 0), cA, voffA); PG8_STAGE(PG8_SB(0, 1), cB + hstep, voffB); PG8_STAGE(PG8_SA(0, 1), cA + hstep, voffA);
;         if (wr == 1) PG8_BAR;
;         PG8_WAIT_V(4); PG8_BAR;
;         PG8_STAGE(PG8_SB(1, 0), cB + kstep, voffB); PG8_STAGE(PG8_SA(1, 0), cA + kstep, voffA); PG8_STAGE(PG8_SB(1, 1), cB + hstep + kstep, voffB);
;         PG8_WAIT_V(6); PG8_BAR;
.LBB0_1607:
	s_cmp_gt_i32 s83, 3
	s_cbranch_scc1 .Lp8_wait_done
	s_min_u32 s2, s33, 32
	s_mov_b64 s[4:5], exec
	v_readlane_b32 s0, v254, 6
	v_readlane_b32 s1, v254, 7
	s_and_b64 s[0:1], s[4:5], s[0:1]
	s_mov_b64 exec, s[0:1]
	s_cbranch_execz .Lp8_wait_join
	v_mov_b32_e32 v2, 0
.Lp8_spin:
	global_load_dword v5, v2, s[96:97] offset:268 sc1
	s_waitcnt vmcnt(0)
	buffer_inv sc1
	v_cmp_gt_u32_e32 vcc, s2, v5
	s_cbranch_vccz .Lp8_wait_join
	s_sleep 4
	s_branch .Lp8_spin
.Lp8_wait_join:
	s_or_b64 exec, exec, s[4:5]
	s_waitcnt vmcnt(0) lgkmcnt(0)
	s_barrier
.Lp8_wait_done:
	v_mov_b32_e32 v10, v0
	s_cmp_lt_i32 s83, 4
	s_cselect_b64 s[20:21], -1, 0
	s_cmp_gt_i32 s83, 3
	v_readfirstlane_b32 s10, v10
	s_cbranch_scc1 .LBB0_1621
	v_lshlrev_b32_e32 v1, 4, v10
	v_add_u32_e32 v2, 0x2000, v1
	v_ashrrev_i32_e32 v3, 31, v2
	v_lshrrev_b32_e32 v3, 22, v3
	v_add_u32_e32 v3, v2, v3
	v_ashrrev_i32_e32 v3, 10, v3
	v_mul_i32_i24_e32 v4, 0x400, v3
	v_sub_u32_e32 v2, v2, v4
	v_lshrrev_b32_e32 v4, 4, v2
	v_bitop3_b32 v2, v4, v2, 32 bitop3:0x6c
	v_ashrrev_i32_e32 v4, 31, v2
	v_lshrrev_b32_e32 v4, 26, v4
	v_add_u32_e32 v4, v2, v4
	v_lshlrev_b32_e32 v6, 3, v3
	v_ashrrev_i32_e32 v5, 6, v4
	v_and_b32_e32 v6, -16, v6
	v_and_b32_e32 v4, 0xc0, v4
	v_add_u32_e32 v6, v5, v6
	v_sub_u32_e32 v2, v2, v4
	v_mov_b32_e32 v4, 1
	v_and_b32_e32 v5, 3, v5
	s_mov_b32 s1, 0x3fffe0
	v_lshrrev_b32_e32 v7, 2, v6
	v_lshlrev_b32_e32 v8, 1, v6
	v_lshlrev_b32_e32 v3, 5, v3
	v_ashrrev_i16_sdwa v2, v4, sext(v2) dst_sel:DWORD dst_unused:UNUSED_PAD src0_sel:DWORD src1_sel:BYTE_0
	v_and_or_b32 v5, v6, s1, v5
	v_and_b32_e32 v7, 4, v7
	v_and_b32_e32 v8, 24, v8
	v_and_b32_e32 v3, 32, v3
	v_bfe_i32 v2, v2, 0, 16
	v_or3_b32 v5, v5, v7, v8
	v_add_lshl_u32 v2, v3, v2, 1
	v_lshl_add_u32 v162, v5, 10, v2
	v_lshl_add_u32 v164, v6, 10, v2
	v_bfe_i32 v2, v10, 27, 1
	v_lshrrev_b32_e32 v2, 22, v2
	v_add_u32_e32 v2, v1, v2
	v_and_b32_e32 v2, 0xfffffc00, v2
	v_sub_u32_e32 v1, v1, v2
	v_lshrrev_b32_e32 v2, 4, v1
	v_ashrrev_i32_e32 v5, 31, v10
	v_bitop3_b32 v1, v2, v1, 32 bitop3:0x6c
	v_lshrrev_b32_e32 v5, 26, v5
	v_ashrrev_i32_e32 v2, 31, v1
	v_add_u32_e32 v5, v10, v5
	v_lshrrev_b32_e32 v2, 26, v2
	v_ashrrev_i32_e32 v5, 6, v5
	v_add_u32_e32 v2, v1, v2
	v_lshlrev_b32_e32 v6, 3, v5
	v_ashrrev_i32_e32 v3, 6, v2
	v_and_b32_e32 v6, -16, v6
	v_add_u32_e32 v6, v3, v6
	v_and_b32_e32 v3, 3, v3
	s_ashr_i32 s6, s10, 6
	v_and_or_b32 v3, v6, s1, v3
	s_ashr_i32 s1, s85, 31
	s_ashr_i32 s11, s10, 8
	s_lshl_b32 s0, s6, 10
	s_lshr_b32 s1, s1, 30
	s_add_u32 s1, s83, s1
	s_addc_u32 s2, s85, 0
	s_and_b32 s3, s1, -4
	s_sub_u32 s50, s83, s3
	s_subb_u32 s51, s85, s2
	s_lshl_b32 s1, s1, 7
	s_movk_i32 s48, 0x100
	s_and_b32 s2, s1, 0xfffffe00
	s_ashr_i32 s3, s2, 31
	s_ashr_i32 s49, s48, 31
	s_lshl_b64 s[2:3], s[2:3], 1
	s_lshl_b64 s[4:5], s[48:49], 18
	s_add_u32 s7, s60, s4
	v_and_b32_e32 v2, 0xc0, v2
	s_addc_u32 s14, s61, s5
	s_lshl_b64 s[4:5], s[50:51], 18
	v_sub_u32_e32 v1, v1, v2
	s_add_u32 s1, s63, s4
	v_lshrrev_b32_e32 v7, 2, v6
	v_lshlrev_b32_e32 v8, 1, v6
	v_lshlrev_b32_e32 v5, 5, v5
	v_ashrrev_i16_sdwa v1, v4, sext(v1) dst_sel:DWORD dst_unused:UNUSED_PAD src0_sel:DWORD src1_sel:BYTE_0
	s_addc_u32 s4, s64, s5
	v_and_b32_e32 v7, 4, v7
	v_and_b32_e32 v8, 24, v8
	v_and_b32_e32 v5, 32, v5
	v_bfe_i32 v1, v1, 0, 16
	s_add_u32 s54, s1, s2
	v_or3_b32 v3, v3, v7, v8
	v_add_lshl_u32 v1, v5, v1, 1
	s_addc_u32 s55, s4, s3
	s_add_i32 s1, s0, 0
	v_lshl_add_u32 v166, v3, 10, v1
	s_add_i32 m0, s1, 0x10000
	v_lshl_add_u32 v168, v6, 10, v1
	global_load_lds_dwordx4 v166, s[54:55]
	s_add_i32 m0, s1, 0x12000
	s_add_u32 s4, s54, 0x20000
	global_load_lds_dwordx4 v162, s[54:55]
	s_addc_u32 s5, s55, 0
	s_add_i32 m0, s1, 0x14000
	v_mov_b32_e32 v167, 0
	global_load_lds_dwordx4 v166, s[4:5]
	s_add_i32 m0, s1, 0x16000
	s_add_u32 s52, s7, s2
	s_addc_u32 s53, s14, s3
	s_add_i32 s2, s1, 0x2000
	global_load_lds_dwordx4 v162, s[4:5]
	s_mov_b32 m0, s1
	s_add_u32 s4, s52, 0x20000
	global_load_lds_dwordx4 v168, s[52:53]
	s_mov_b32 m0, s2
	s_addc_u32 s5, s53, 0
	s_add_i32 s3, s1, 0x4000
	global_load_lds_dwordx4 v164, s[52:53]
	s_mov_b32 m0, s3
	s_add_i32 s51, s1, 0x6000
	global_load_lds_dwordx4 v168, s[4:5]
	s_mov_b32 m0, s51
	v_mov_b32_e32 v163, v167
	global_load_lds_dwordx4 v164, s[4:5]
	v_mov_b32_e32 v169, v167
	v_mov_b32_e32 v165, v167
	s_cmp_eq_u32 s11, 1
	v_lshl_add_u64 v[8:9], s[54:55], 0, v[166:167]
	v_lshl_add_u64 v[6:7], s[54:55], 0, v[162:163]
	v_lshl_add_u64 v[2:3], s[52:53], 0, v[168:169]
	s_cselect_b64 s[4:5], -1, 0
	s_cmp_lg_u32 s11, 1
	v_lshl_add_u64 v[4:5], s[52:53], 0, v[164:165]
	s_cbranch_scc1 .LBB0_1610
	s_barrier
